# DeltaNet conv+silu section rewritten by hand: all LDS reads in flight, masking only in boundary chunks, interleaved silu chains
# speedup vs baseline: 1.0143x; 1.0143x over previous
; __device__ __forceinline__ float bflo(unsigned u) { return __uint_as_float(u << 16); }
; __device__ __forceinline__ float bfhi(unsigned u) { return __uint_as_float(u & 0xffff0000u); }
; __device__ __forceinline__ float silu(float x) { return x * sigm(x); }
; __device__ __forceinline__ void dn_task(const Params& p, int l, int task, char* smem) {
;     ...
;     if (tid < 192) {
;       const int c4 = tid % 48, tg = tid / 48, part = c4 >> 4, cc = (c4 & 15) * 4;
;       float4 w[5];
; #pragma unroll
;       for (int j = 0; j < 5; ++j) w[j] = *(const float4*)(wl + j * 192 + c4 * 4);
;       float x0[12], x1[12], x2[12], x3[12];
; #pragma unroll
;       for (int r = 0; r < 12; ++r) {
;         const int pp = plo + tg * 8 + r - 2;
;         u32x2 rr = *(const u32x2*)(rawb + (tg * 8 + r) * 192 + c4 * 4);
;         const bool ok = (pp >= 0) && (pp < len);
;         rr.x = ok ? rr.x : 0u; rr.y = ok ? rr.y : 0u;
;         x0[r] = bflo(rr.x); x1[r] = bfhi(rr.x); x2[r] = bflo(rr.y); x3[r] = bfhi(rr.y);
;       }
;       float* dbase = (part == 0) ? (qs + cc) : (part == 1) ? (ks + cc) : (vs + cc);
;       const int dstride = (part == 2) ? 64 : 68;
; #pragma unroll
;       for (int uu = 0; uu < 8; ++uu) {
;         float a0 = 0.f, a1 = 0.f, a2 = 0.f, a3 = 0.f;
; #pragma unroll
;         for (int j = 0; j < 5; ++j) {
;           a0 += w[j].x * x0[uu + j]; a1 += w[j].y * x1[uu + j]; a2 += w[j].z * x2[uu + j]; a3 += w[j].w * x3[uu + j];
;         }
;         const int u = tg * 8 + uu, t = dir ? 31 - u : u;
;         float4 o4; o4.x = silu(a0); o4.y = silu(a1); o4.z = silu(a2); o4.w = silu(a3);
;         *(float4*)(dbase + t * dstride) = o4;
;       }
.LBB0_193:
	s_lshl_b32 s70, s81, 5
	s_add_i32 s71, s70, 0xffffff00
	s_cmp_lt_u32 s81, 8
	s_cselect_b64 s[68:69], -1, 0
	s_and_b64 s[60:61], s[68:69], exec
	s_cselect_b32 s82, 0x100, s19
	s_cselect_b32 s87, s70, s71
	s_sub_i32 s60, s82, s87
	s_sub_i32 s70, s60, 32
	s_and_b64 s[60:61], s[40:41], exec
	s_cselect_b32 s98, s87, s70
	s_and_saveexec_b64 s[70:71], s[52:53]
	s_cbranch_execz .LBB0_195
	ds_read_b128 v[58:61], v168 offset:26112
	ds_read_b128 v[62:65], v168 offset:26880
	ds_read_b128 v[66:69], v168 offset:27648
	ds_read_b128 v[70:73], v168 offset:28416
	ds_read_b128 v[74:77], v168 offset:29184
	ds_read_b64 v[12:13], v214 offset:29952
	ds_read_b64 v[16:17], v214 offset:30336
	ds_read_b64 v[20:21], v214 offset:30720
	ds_read_b64 v[24:25], v214 offset:31104
	ds_read_b64 v[28:29], v214 offset:31488
	ds_read_b64 v[32:33], v214 offset:31872
	ds_read_b64 v[36:37], v214 offset:32256
	ds_read_b64 v[40:41], v214 offset:32640
	ds_read_b64 v[44:45], v214 offset:33024
	ds_read_b64 v[48:49], v214 offset:33408
	ds_read_b64 v[52:53], v214 offset:33792
	ds_read_b64 v[56:57], v214 offset:34176
	s_mov_b32 s60, 0xbfb8aa3b
	s_cmp_lt_u32 s98, 2
	s_cbranch_scc1 .Ldnc_mask
	s_add_i32 s61, s98, 34
	s_cmp_gt_u32 s61, s82
	s_cbranch_scc0 .Ldnc_go
.Ldnc_mask:
	v_add_u32_e32 v78, s98, v169
	v_add_u32_e32 v78, -2, v78
	s_waitcnt lgkmcnt(0)
	v_cmp_gt_u32_e32 vcc, s82, v78
	v_cndmask_b32_e32 v12, 0, v12, vcc
	v_cndmask_b32_e32 v13, 0, v13, vcc
	v_add_u32_e32 v79, 1, v78
	v_cmp_gt_u32_e32 vcc, s82, v79
	v_cndmask_b32_e32 v16, 0, v16, vcc
	v_cndmask_b32_e32 v17, 0, v17, vcc
	v_add_u32_e32 v79, 2, v78
	v_cmp_gt_u32_e32 vcc, s82, v79
	v_cndmask_b32_e32 v20, 0, v20, vcc
	v_cndmask_b32_e32 v21, 0, v21, vcc
	v_add_u32_e32 v79, 3, v78
	v_cmp_gt_u32_e32 vcc, s82, v79
	v_cndmask_b32_e32 v24, 0, v24, vcc
	v_cndmask_b32_e32 v25, 0, v25, vcc
	v_add_u32_e32 v79, 4, v78
	v_cmp_gt_u32_e32 vcc, s82, v79
	v_cndmask_b32_e32 v28, 0, v28, vcc
	v_cndmask_b32_e32 v29, 0, v29, vcc
	v_add_u32_e32 v79, 5, v78
	v_cmp_gt_u32_e32 vcc, s82, v79
	v_cndmask_b32_e32 v32, 0, v32, vcc
	v_cndmask_b32_e32 v33, 0, v33, vcc
	v_add_u32_e32 v79, 6, v78
	v_cmp_gt_u32_e32 vcc, s82, v79
	v_cndmask_b32_e32 v36, 0, v36, vcc
	v_cndmask_b32_e32 v37, 0, v37, vcc
	v_add_u32_e32 v79, 7, v78
	v_cmp_gt_u32_e32 vcc, s82, v79
	v_cndmask_b32_e32 v40, 0, v40, vcc
	v_cndmask_b32_e32 v41, 0, v41, vcc
	v_add_u32_e32 v79, 8, v78
	v_cmp_gt_u32_e32 vcc, s82, v79
	v_cndmask_b32_e32 v44, 0, v44, vcc
	v_cndmask_b32_e32 v45, 0, v45, vcc
	v_add_u32_e32 v79, 9, v78
	v_cmp_gt_u32_e32 vcc, s82, v79
	v_cndmask_b32_e32 v48, 0, v48, vcc
	v_cndmask_b32_e32 v49, 0, v49, vcc
	v_add_u32_e32 v79, 10, v78
	v_cmp_gt_u32_e32 vcc, s82, v79
	v_cndmask_b32_e32 v52, 0, v52, vcc
	v_cndmask_b32_e32 v53, 0, v53, vcc
	v_add_u32_e32 v79, 11, v78
	v_cmp_gt_u32_e32 vcc, s82, v79
	v_cndmask_b32_e32 v56, 0, v56, vcc
	v_cndmask_b32_e32 v57, 0, v57, vcc
.Ldnc_go:
	s_waitcnt lgkmcnt(7)
	v_lshlrev_b32_e32 v10, 16, v12
	v_and_b32_e32 v11, 0xffff0000, v12
	v_lshlrev_b32_e32 v12, 16, v13
	v_and_b32_e32 v13, 0xffff0000, v13
	v_lshlrev_b32_e32 v14, 16, v16
	v_and_b32_e32 v15, 0xffff0000, v16
	v_lshlrev_b32_e32 v16, 16, v17
	v_and_b32_e32 v17, 0xffff0000, v17
	v_lshlrev_b32_e32 v18, 16, v20
	v_and_b32_e32 v19, 0xffff0000, v20
	v_lshlrev_b32_e32 v20, 16, v21
	v_and_b32_e32 v21, 0xffff0000, v21
	v_lshlrev_b32_e32 v22, 16, v24
	v_and_b32_e32 v23, 0xffff0000, v24
	v_lshlrev_b32_e32 v24, 16, v25
	v_and_b32_e32 v25, 0xffff0000, v25
	v_lshlrev_b32_e32 v26, 16, v28
	v_and_b32_e32 v27, 0xffff0000, v28
	v_lshlrev_b32_e32 v28, 16, v29
	v_and_b32_e32 v29, 0xffff0000, v29
	s_waitcnt lgkmcnt(0)
	v_pk_fma_f32 v[226:227], v[58:59], v[10:11], 0 op_sel_hi:[1,1,0]
	v_lshlrev_b32_e32 v30, 16, v32
	v_pk_fma_f32 v[228:229], v[60:61], v[12:13], 0 op_sel_hi:[1,1,0]
	v_and_b32_e32 v31, 0xffff0000, v32
	v_pk_fma_f32 v[226:227], v[62:63], v[14:15], v[226:227]
	v_lshlrev_b32_e32 v32, 16, v33
	v_pk_fma_f32 v[228:229], v[64:65], v[16:17], v[228:229]
	v_and_b32_e32 v33, 0xffff0000, v33
	v_pk_fma_f32 v[226:227], v[66:67], v[18:19], v[226:227]
	v_lshlrev_b32_e32 v34, 16, v36
	v_pk_fma_f32 v[228:229], v[68:69], v[20:21], v[228:229]
	v_and_b32_e32 v35, 0xffff0000, v36
	v_pk_fma_f32 v[226:227], v[70:71], v[22:23], v[226:227]
	v_lshlrev_b32_e32 v36, 16, v37
	v_pk_fma_f32 v[228:229], v[72:73], v[24:25], v[228:229]
	v_and_b32_e32 v37, 0xffff0000, v37
	v_pk_fma_f32 v[226:227], v[74:75], v[26:27], v[226:227]
	v_lshlrev_b32_e32 v38, 16, v40
	v_pk_fma_f32 v[228:229], v[76:77], v[28:29], v[228:229]
	v_and_b32_e32 v39, 0xffff0000, v40
	v_lshlrev_b32_e32 v40, 16, v41
	v_and_b32_e32 v41, 0xffff0000, v41
	v_lshlrev_b32_e32 v42, 16, v44
	v_and_b32_e32 v43, 0xffff0000, v44
	v_lshlrev_b32_e32 v44, 16, v45
	v_and_b32_e32 v45, 0xffff0000, v45
	v_lshlrev_b32_e32 v46, 16, v48
	v_and_b32_e32 v47, 0xffff0000, v48
	v_lshlrev_b32_e32 v48, 16, v49
	v_and_b32_e32 v49, 0xffff0000, v49
	v_lshlrev_b32_e32 v50, 16, v52
	v_and_b32_e32 v51, 0xffff0000, v52
	v_lshlrev_b32_e32 v52, 16, v53
	v_and_b32_e32 v53, 0xffff0000, v53
	v_lshlrev_b32_e32 v54, 16, v56
	v_and_b32_e32 v55, 0xffff0000, v56
	v_lshlrev_b32_e32 v56, 16, v57
	v_and_b32_e32 v57, 0xffff0000, v57
	v_pk_mul_f32 v[230:231], v[226:227], s[60:61] op_sel_hi:[1,0]
	v_pk_fma_f32 v[234:235], v[58:59], v[14:15], 0 op_sel_hi:[1,1,0]
	v_pk_mul_f32 v[232:233], v[228:229], s[60:61] op_sel_hi:[1,0]
	v_pk_fma_f32 v[236:237], v[60:61], v[16:17], 0 op_sel_hi:[1,1,0]
	v_exp_f32_e32 v230, v230
	v_pk_fma_f32 v[234:235], v[62:63], v[18:19], v[234:235]
	v_exp_f32_e32 v231, v231
	v_pk_fma_f32 v[236:237], v[64:65], v[20:21], v[236:237]
	v_exp_f32_e32 v232, v232
	v_pk_fma_f32 v[234:235], v[66:67], v[22:23], v[234:235]
; __device__ __forceinline__ float silu(float x) { return x * sigm(x); }
; __device__ __forceinline__ void dn_task(const Params& p, int l, int task, char* smem) {
;     ...
; #pragma unroll
;       for (int uu = 0; uu < 8; ++uu) {
;         float a0 = 0.f, a1 = 0.f, a2 = 0.f, a3 = 0.f;
; #pragma unroll
;         for (int j = 0; j < 5; ++j) {
;           a0 += w[j].x * x0[uu + j]; a1 += w[j].y * x1[uu + j]; a2 += w[j].z * x2[uu + j]; a3 += w[j].w * x3[uu + j];
;         }
;         const int u = tg * 8 + uu, t = dir ? 31 - u : u;
;         float4 o4; o4.x = silu(a0); o4.y = silu(a1); o4.z = silu(a2); o4.w = silu(a3);
;         *(float4*)(dbase + t * dstride) = o4;
;       }
	v_exp_f32_e32 v233, v233
	v_pk_fma_f32 v[236:237], v[68:69], v[24:25], v[236:237]
	v_pk_add_f32 v[230:231], v[230:231], 1.0 op_sel_hi:[1,0]
	v_pk_fma_f32 v[234:235], v[70:71], v[26:27], v[234:235]
	v_pk_add_f32 v[232:233], v[232:233], 1.0 op_sel_hi:[1,0]
	v_pk_fma_f32 v[236:237], v[72:73], v[28:29], v[236:237]
	v_rcp_f32_e32 v230, v230
	v_pk_fma_f32 v[234:235], v[74:75], v[30:31], v[234:235]
	v_rcp_f32_e32 v231, v231
	v_pk_fma_f32 v[236:237], v[76:77], v[32:33], v[236:237]
	v_rcp_f32_e32 v232, v232
	v_rcp_f32_e32 v233, v233
	v_pk_mul_f32 v[226:227], v[226:227], v[230:231]
	v_pk_mul_f32 v[228:229], v[228:229], v[232:233]
	ds_write_b128 v199, v[226:229]
	v_pk_mul_f32 v[238:239], v[234:235], s[60:61] op_sel_hi:[1,0]
	v_pk_fma_f32 v[226:227], v[58:59], v[18:19], 0 op_sel_hi:[1,1,0]
	v_pk_mul_f32 v[240:241], v[236:237], s[60:61] op_sel_hi:[1,0]
	v_pk_fma_f32 v[228:229], v[60:61], v[20:21], 0 op_sel_hi:[1,1,0]
	v_exp_f32_e32 v238, v238
	v_pk_fma_f32 v[226:227], v[62:63], v[22:23], v[226:227]
	v_exp_f32_e32 v239, v239
	v_pk_fma_f32 v[228:229], v[64:65], v[24:25], v[228:229]
	v_exp_f32_e32 v240, v240
	v_pk_fma_f32 v[226:227], v[66:67], v[26:27], v[226:227]
	v_exp_f32_e32 v241, v241
	v_pk_fma_f32 v[228:229], v[68:69], v[28:29], v[228:229]
	v_pk_add_f32 v[238:239], v[238:239], 1.0 op_sel_hi:[1,0]
	v_pk_fma_f32 v[226:227], v[70:71], v[30:31], v[226:227]
	v_pk_add_f32 v[240:241], v[240:241], 1.0 op_sel_hi:[1,0]
	v_pk_fma_f32 v[228:229], v[72:73], v[32:33], v[228:229]
	v_rcp_f32_e32 v238, v238
	v_pk_fma_f32 v[226:227], v[74:75], v[34:35], v[226:227]
	v_rcp_f32_e32 v239, v239
	v_pk_fma_f32 v[228:229], v[76:77], v[36:37], v[228:229]
	v_rcp_f32_e32 v240, v240
	v_rcp_f32_e32 v241, v241
	v_pk_mul_f32 v[234:235], v[234:235], v[238:239]
	v_pk_mul_f32 v[236:237], v[236:237], v[240:241]
	ds_write_b128 v200, v[234:237]
	v_pk_mul_f32 v[230:231], v[226:227], s[60:61] op_sel_hi:[1,0]
	v_pk_fma_f32 v[234:235], v[58:59], v[22:23], 0 op_sel_hi:[1,1,0]
	v_pk_mul_f32 v[232:233], v[228:229], s[60:61] op_sel_hi:[1,0]
	v_pk_fma_f32 v[236:237], v[60:61], v[24:25], 0 op_sel_hi:[1,1,0]
	v_exp_f32_e32 v230, v230
	v_pk_fma_f32 v[234:235], v[62:63], v[26:27], v[234:235]
	v_exp_f32_e32 v231, v231
	v_pk_fma_f32 v[236:237], v[64:65], v[28:29], v[236:237]
	v_exp_f32_e32 v232, v232
	v_pk_fma_f32 v[234:235], v[66:67], v[30:31], v[234:235]
	v_exp_f32_e32 v233, v233
	v_pk_fma_f32 v[236:237], v[68:69], v[32:33], v[236:237]
	v_pk_add_f32 v[230:231], v[230:231], 1.0 op_sel_hi:[1,0]
	v_pk_fma_f32 v[234:235], v[70:71], v[34:35], v[234:235]
	v_pk_add_f32 v[232:233], v[232:233], 1.0 op_sel_hi:[1,0]
	v_pk_fma_f32 v[236:237], v[72:73], v[36:37], v[236:237]
	v_rcp_f32_e32 v230, v230
	v_pk_fma_f32 v[234:235], v[74:75], v[38:39], v[234:235]
	v_rcp_f32_e32 v231, v231
	v_pk_fma_f32 v[236:237], v[76:77], v[40:41], v[236:237]
	v_rcp_f32_e32 v232, v232
	v_rcp_f32_e32 v233, v233
	v_pk_mul_f32 v[226:227], v[226:227], v[230:231]
	v_pk_mul_f32 v[228:229], v[228:229], v[232:233]
	ds_write_b128 v201, v[226:229]
	v_pk_mul_f32 v[238:239], v[234:235], s[60:61] op_sel_hi:[1,0]
	v_pk_fma_f32 v[226:227], v[58:59], v[26:27], 0 op_sel_hi:[1,1,0]
	v_pk_mul_f32 v[240:241], v[236:237], s[60:61] op_sel_hi:[1,0]
	v_pk_fma_f32 v[228:229], v[60:61], v[28:29], 0 op_sel_hi:[1,1,0]
	v_exp_f32_e32 v238, v238
	v_pk_fma_f32 v[226:227], v[62:63], v[30:31], v[226:227]
	v_exp_f32_e32 v239, v239
	v_pk_fma_f32 v[228:229], v[64:65], v[32:33], v[228:229]
	v_exp_f32_e32 v240, v240
	v_pk_fma_f32 v[226:227], v[66:67], v[34:35], v[226:227]
	v_exp_f32_e32 v241, v241
	v_pk_fma_f32 v[228:229], v[68:69], v[36:37], v[228:229]
	v_pk_add_f32 v[238:239], v[238:239], 1.0 op_sel_hi:[1,0]
	v_pk_fma_f32 v[226:227], v[70:71], v[38:39], v[226:227]
	v_pk_add_f32 v[240:241], v[240:241], 1.0 op_sel_hi:[1,0]
	v_pk_fma_f32 v[228:229], v[72:73], v[40:41], v[228:229]
	v_rcp_f32_e32 v238, v238
	v_pk_fma_f32 v[226:227], v[74:75], v[42:43], v[226:227]
	v_rcp_f32_e32 v239, v239
	v_pk_fma_f32 v[228:229], v[76:77], v[44:45], v[228:229]
	v_rcp_f32_e32 v240, v240
	v_rcp_f32_e32 v241, v241
	v_pk_mul_f32 v[234:235], v[234:235], v[238:239]
	v_pk_mul_f32 v[236:237], v[236:237], v[240:241]
; __device__ __forceinline__ float silu(float x) { return x * sigm(x); }
; __device__ __forceinline__ void dn_task(const Params& p, int l, int task, char* smem) {
;     ...
; #pragma unroll
;       for (int uu = 0; uu < 8; ++uu) {
;         float a0 = 0.f, a1 = 0.f, a2 = 0.f, a3 = 0.f;
; #pragma unroll
;         for (int j = 0; j < 5; ++j) {
;           a0 += w[j].x * x0[uu + j]; a1 += w[j].y * x1[uu + j]; a2 += w[j].z * x2[uu + j]; a3 += w[j].w * x3[uu + j];
;         }
;         const int u = tg * 8 + uu, t = dir ? 31 - u : u;
;         float4 o4; o4.x = silu(a0); o4.y = silu(a1); o4.z = silu(a2); o4.w = silu(a3);
;         *(float4*)(dbase + t * dstride) = o4;
;       }
	ds_write_b128 v202, v[234:237]
	v_pk_mul_f32 v[230:231], v[226:227], s[60:61] op_sel_hi:[1,0]
	v_pk_fma_f32 v[234:235], v[58:59], v[30:31], 0 op_sel_hi:[1,1,0]
	v_pk_mul_f32 v[232:233], v[228:229], s[60:61] op_sel_hi:[1,0]
	v_pk_fma_f32 v[236:237], v[60:61], v[32:33], 0 op_sel_hi:[1,1,0]
	v_exp_f32_e32 v230, v230
	v_pk_fma_f32 v[234:235], v[62:63], v[34:35], v[234:235]
	v_exp_f32_e32 v231, v231
	v_pk_fma_f32 v[236:237], v[64:65], v[36:37], v[236:237]
	v_exp_f32_e32 v232, v232
	v_pk_fma_f32 v[234:235], v[66:67], v[38:39], v[234:235]
	v_exp_f32_e32 v233, v233
	v_pk_fma_f32 v[236:237], v[68:69], v[40:41], v[236:237]
	v_pk_add_f32 v[230:231], v[230:231], 1.0 op_sel_hi:[1,0]
	v_pk_fma_f32 v[234:235], v[70:71], v[42:43], v[234:235]
	v_pk_add_f32 v[232:233], v[232:233], 1.0 op_sel_hi:[1,0]
	v_pk_fma_f32 v[236:237], v[72:73], v[44:45], v[236:237]
	v_rcp_f32_e32 v230, v230
	v_pk_fma_f32 v[234:235], v[74:75], v[46:47], v[234:235]
	v_rcp_f32_e32 v231, v231
	v_pk_fma_f32 v[236:237], v[76:77], v[48:49], v[236:237]
	v_rcp_f32_e32 v232, v232
	v_rcp_f32_e32 v233, v233
	v_pk_mul_f32 v[226:227], v[226:227], v[230:231]
	v_pk_mul_f32 v[228:229], v[228:229], v[232:233]
	ds_write_b128 v203, v[226:229]
	v_pk_mul_f32 v[238:239], v[234:235], s[60:61] op_sel_hi:[1,0]
	v_pk_fma_f32 v[226:227], v[58:59], v[34:35], 0 op_sel_hi:[1,1,0]
	v_pk_mul_f32 v[240:241], v[236:237], s[60:61] op_sel_hi:[1,0]
	v_pk_fma_f32 v[228:229], v[60:61], v[36:37], 0 op_sel_hi:[1,1,0]
	v_exp_f32_e32 v238, v238
	v_pk_fma_f32 v[226:227], v[62:63], v[38:39], v[226:227]
	v_exp_f32_e32 v239, v239
	v_pk_fma_f32 v[228:229], v[64:65], v[40:41], v[228:229]
	v_exp_f32_e32 v240, v240
	v_pk_fma_f32 v[226:227], v[66:67], v[42:43], v[226:227]
	v_exp_f32_e32 v241, v241
	v_pk_fma_f32 v[228:229], v[68:69], v[44:45], v[228:229]
	v_pk_add_f32 v[238:239], v[238:239], 1.0 op_sel_hi:[1,0]
	v_pk_fma_f32 v[226:227], v[70:71], v[46:47], v[226:227]
	v_pk_add_f32 v[240:241], v[240:241], 1.0 op_sel_hi:[1,0]
	v_pk_fma_f32 v[228:229], v[72:73], v[48:49], v[228:229]
	v_rcp_f32_e32 v238, v238
	v_pk_fma_f32 v[226:227], v[74:75], v[50:51], v[226:227]
	v_rcp_f32_e32 v239, v239
	v_pk_fma_f32 v[228:229], v[76:77], v[52:53], v[228:229]
	v_rcp_f32_e32 v240, v240
	v_rcp_f32_e32 v241, v241
	v_pk_mul_f32 v[234:235], v[234:235], v[238:239]
	v_pk_mul_f32 v[236:237], v[236:237], v[240:241]
	ds_write_b128 v204, v[234:237]
	v_pk_mul_f32 v[230:231], v[226:227], s[60:61] op_sel_hi:[1,0]
	v_pk_fma_f32 v[234:235], v[58:59], v[38:39], 0 op_sel_hi:[1,1,0]
	v_pk_mul_f32 v[232:233], v[228:229], s[60:61] op_sel_hi:[1,0]
	v_pk_fma_f32 v[236:237], v[60:61], v[40:41], 0 op_sel_hi:[1,1,0]
	v_exp_f32_e32 v230, v230
	v_pk_fma_f32 v[234:235], v[62:63], v[42:43], v[234:235]
	v_exp_f32_e32 v231, v231
	v_pk_fma_f32 v[236:237], v[64:65], v[44:45], v[236:237]
	v_exp_f32_e32 v232, v232
	v_pk_fma_f32 v[234:235], v[66:67], v[46:47], v[234:235]
	v_exp_f32_e32 v233, v233
	v_pk_fma_f32 v[236:237], v[68:69], v[48:49], v[236:237]
	v_pk_add_f32 v[230:231], v[230:231], 1.0 op_sel_hi:[1,0]
	v_pk_fma_f32 v[234:235], v[70:71], v[50:51], v[234:235]
	v_pk_add_f32 v[232:233], v[232:233], 1.0 op_sel_hi:[1,0]
	v_pk_fma_f32 v[236:237], v[72:73], v[52:53], v[236:237]
	v_rcp_f32_e32 v230, v230
	v_pk_fma_f32 v[234:235], v[74:75], v[54:55], v[234:235]
	v_rcp_f32_e32 v231, v231
	v_pk_fma_f32 v[236:237], v[76:77], v[56:57], v[236:237]
	v_rcp_f32_e32 v232, v232
	v_rcp_f32_e32 v233, v233
	v_pk_mul_f32 v[226:227], v[226:227], v[230:231]
	v_pk_mul_f32 v[228:229], v[228:229], v[232:233]
	ds_write_b128 v205, v[226:229]
	v_pk_mul_f32 v[238:239], v[234:235], s[60:61] op_sel_hi:[1,0]
	v_pk_mul_f32 v[240:241], v[236:237], s[60:61] op_sel_hi:[1,0]
	v_exp_f32_e32 v238, v238
	v_exp_f32_e32 v239, v239
	v_exp_f32_e32 v240, v240
	v_exp_f32_e32 v241, v241
	v_pk_add_f32 v[238:239], v[238:239], 1.0 op_sel_hi:[1,0]
	v_pk_add_f32 v[240:241], v[240:241], 1.0 op_sel_hi:[1,0]
	v_rcp_f32_e32 v238, v238
	v_rcp_f32_e32 v239, v239
	v_rcp_f32_e32 v240, v240
	v_rcp_f32_e32 v241, v241
	v_pk_mul_f32 v[234:235], v[234:235], v[238:239]
	v_pk_mul_f32 v[236:237], v[236:237], v[240:241]
	ds_write_b128 v206, v[234:237]
